# phase-0 seam uses the XCD barrier instead of cooperative-groups grid.sync (all seams now use the same barrier); plus earlier K-loop/S5a/final-norm edits
# speedup vs baseline: 1.0076x; 1.0012x over previous
; __device__ __forceinline__ void xcd_barrier(const XcdBarrier& b) {
;     asm volatile("s_waitcnt vmcnt(0)" ::: "memory");
;     __syncthreads();
;     if (threadIdx.x == 0) {
;         unsigned* bar = b.bar;
;         __builtin_amdgcn_s_waitcnt(0);
;         unsigned nloc = b.st[0], nx = b.st[1];
;         if (nloc == 0u) { xcd_barrier_complete(bar, b.x, nloc, nx); b.st[0] = nloc; b.st[1] = nx; }
; __global__ void __launch_bounds__(512, 2) hybrid_fwd(Params p0) {
;     ...
;         if (rep + 1 < reps || ph + 1 < ph_hi) {
;             if (ph == ph_lo && rep == 0) grid.sync();
;             else { xb.bar = (unsigned*)(p.ws + WS_BAR); xcd_barrier(xb); } }
.LBB0_787:
	s_cmp_lg_u32 s93, -1
	s_waitcnt lgkmcnt(0)
	s_mov_b64 s[4:5], -1
	s_cbranch_scc0 .LBB0_844
	s_waitcnt vmcnt(0)
	s_waitcnt vmcnt(0)
	s_barrier
	s_mov_b64 s[4:5], exec
	v_readlane_b32 s6, v253, 4
	v_readlane_b32 s7, v253, 5
	s_and_b64 s[6:7], s[4:5], s[6:7]
	s_mov_b64 exec, s[6:7]
	s_cbranch_execz .LBB0_843
	s_add_i32 s29, 0, 0x20000
	v_mov_b32_e32 v0, s29
	s_waitcnt vmcnt(0) expcnt(0) lgkmcnt(0)
	ds_read_b32 v3, v0
	v_readlane_b32 s2, v253, 39
	s_waitcnt lgkmcnt(0)
	v_cmp_ne_u32_e32 vcc, 0, v3
	v_mov_b32_e32 v0, s2
	ds_read_b32 v2, v0
	s_cbranch_vccnz .LBB0_807
	s_add_u32 s6, s36, 0x1e478200
	s_addc_u32 s7, s37, 0
	s_add_u32 s8, s36, 0x1e478400
	s_addc_u32 s9, s37, 0
	s_add_u32 s10, s36, 0x1e478500
	s_addc_u32 s11, s37, 0
	s_add_u32 s12, s36, 0x1e478600
	s_addc_u32 s13, s37, 0
	s_add_u32 s14, s36, 0x1e478700
	s_addc_u32 s15, s37, 0
	s_add_u32 s16, s36, 0x1e478800
	s_addc_u32 s17, s37, 0
	s_add_u32 s18, s36, 0x1e478900
	s_addc_u32 s19, s37, 0
	s_add_u32 s20, s36, 0x1e478a00
	s_addc_u32 s21, s37, 0
	s_add_u32 s22, s36, 0x1e478b00
	s_addc_u32 s23, s37, 0
	s_add_u32 s40, s36, 0x1e478c00
	s_addc_u32 s41, s37, 0
	s_add_u32 s42, s36, 0x1e478d00
	s_addc_u32 s43, s37, 0
	s_add_u32 s44, s36, 0x1e478e00
	s_addc_u32 s45, s37, 0
	s_add_u32 s46, s36, 0x1e478f00
	s_addc_u32 s47, s37, 0
	s_add_u32 s48, s36, 0x1e479000
	s_addc_u32 s49, s37, 0
	s_add_u32 s50, s36, 0x1e479100
	s_addc_u32 s51, s37, 0
	s_add_u32 s52, s36, 0x1e479200
	s_addc_u32 s53, s37, 0
	s_add_u32 s54, s36, 0x1e479300
	s_addc_u32 s55, s37, 0
	s_mov_b32 s30, 1
	s_branch .LBB0_792
